# ALIGN_EPI barriers for EpiResid GEMMs (FFN-out, mixer-out): both wave halves run the residual epilogue together
# speedup vs baseline: 1.0001x; 1.0001x over previous
; #define PG8_BAR __builtin_amdgcn_s_barrier()
;     __host__ __device__ bool next(int i, Unit& u) const {
;         const long L = (long)i * G + c; if (L >= nwg) return false;
;         int wgid = (int)L; { const int q = nwg / NXCD, r = nwg % NXCD, xcd = wgid % NXCD, off = wgid / NXCD; wgid = (xcd < r ? xcd * (q + 1) : r * (q + 1) + (xcd - r) * q) + off; }
;         const int nig = WGM * nN, gid = wgid / nig, fm = gid * WGM, gsz = (nM - fm) < WGM ? (nM - fm) : WGM;
;         u.pm = fm + ((wgid % nig) % gsz); u.pn = (wgid % nig) / gsz; return true;
; template <class Epi, class Sched, int KC, bool ALIGN_EPI = false, bool SP2 = false, bool ATILED = false>
; __device__ __forceinline__ void gemm_phase(LAS unsigned char* lds, const Gemm g, const Sched& S, const Epi& E, int wave_s) {
;     ...
;         if (!has_next) break;
; #pragma unroll
;         for (int a = 0; a < 2; ++a)
; #pragma unroll
;             for (int b = 0; b < 2; ++b)
; #pragma unroll
;                 for (int m = 0; m < 4; ++m)
; #pragma unroll
;                     for (int n = 0; n < 2; ++n) acc[a][b][m][n] = (f32x4){0.f, 0.f, 0.f, 0.f};
;         cur = nxt; cA = nA; cB = nB; ++ui;
;         if constexpr (ALIGN_EPI) { if (wr == 1) PG8_BAR; }
.LBB0_306:
	s_or_b64 exec, exec, s[8:9]
	s_and_b64 vcc, exec, s[6:7]
	s_mov_b32 s18, s48
	s_mov_b32 s19, s49
	s_mov_b64 s[22:23], s[10:11]
	s_mov_b64 s[20:21], s[16:17]
	s_cbranch_vccnz .LBB0_367
	s_cmpk_lt_u32 s28, 0x100
	s_cbranch_scc1 .Lffo_next
	s_barrier
.Lffo_next:
.LBB0_307:
	s_add_i32 s45, s45, 1
	s_mul_i32 s6, s45, s46
	s_mul_hi_u32 s7, s45, s26
	s_add_i32 s7, s7, s6
	s_mul_i32 s6, s45, s26
	s_add_u32 s10, s6, s27
	s_addc_u32 s11, s7, s47
	v_mov_b64_e32 v[2:3], 0x200
	v_cmp_lt_i64_e64 s[8:9], s[10:11], v[2:3]
	v_mov_b64_e32 v[2:3], 0x1ff
	v_cmp_gt_i64_e64 s[6:7], s[10:11], v[2:3]
	s_and_b64 vcc, exec, s[6:7]
	s_cbranch_vccnz .LBB0_313
	s_ashr_i32 s11, s10, 31
	s_lshr_b32 s11, s11, 29
	s_add_i32 s16, s10, s11
	s_and_b32 s11, s16, -8
	s_sub_i32 s17, s10, s11
	s_cmp_gt_i32 s17, -1
	s_mov_b64 s[10:11], -1
	s_cbranch_scc0 .LBB0_310
	s_lshl_b32 s24, s17, 6
	s_mov_b64 s[10:11], 0

; #define PG8_STAGE(bufoff, gbase, voff) do { _Pragma("unroll") for (int _i = 0; _i < 2; ++_i) \
;         __builtin_amdgcn_global_load_lds((const unsigned*)((const char*)(gbase) + (voff)[_i]), (LAS unsigned*)(lds + (bufoff) + ldsw + _i * 8192), 16, 0, 0); } while (0)
; #define PG8_LDA(dst, b, h) do { _Pragma("unroll") for (int m = 0; m < 4; ++m) _Pragma("unroll") for (int k = 0; k < 2; ++k) dst[m][k] = *(const LAS bf16x8*)(lds + PG8_SA(b, h) + aoff + m * 2048 + k * 1024); } while (0)
; #define PG8_LDB(dst, b, h) do { _Pragma("unroll") for (int n = 0; n < 2; ++n) _Pragma("unroll") for (int k = 0; k < 2; ++k) dst[n][k] = *(const LAS bf16x8*)(lds + PG8_SB(b, h) + boff + n * 2048 + k * 1024); } while (0)
; #define PG8_MMA(ai, bj, At, Bt) do { __builtin_amdgcn_s_setprio(1); _Pragma("unroll") for (int m = 0; m < 4; ++m) _Pragma("unroll") for (int n = 0; n < 2; ++n) _Pragma("unroll") for (int k = 0; k < 2; ++k) \
;         acc[ai][bj][m][n] = __builtin_amdgcn_mfma_f32_16x16x32_bf16(Bt[n][k], At[m][k], acc[ai][bj][m][n], 0, 0, 0); __builtin_amdgcn_s_setprio(0); } while (0)
; #define PG8_WAIT_V(n) asm volatile("s_waitcnt vmcnt(" #n ")" ::: "memory")
; #define PG8_BAR __builtin_amdgcn_s_barrier()
; template <class Epi, class Sched, int KC, bool ALIGN_EPI = false, bool SP2 = false, bool ATILED = false>
; __device__ __forceinline__ void gemm_phase(LAS unsigned char* lds, const Gemm g, const Sched& S, const Epi& E, int wave_s) {
;     ...
;         for (int t = 0; t < nt; t += 2) {
;             const bool last = (t == nt - 2);
;             const char* a1 = cA + PG8_AOFF(t + 1);
;             const char* a2 = last ? nA : cA + PG8_AOFF(t + 2); const char* b2 = last ? nB : cB + (size_t)(t + 2) * kstep;
;             const char* a3 = a2 + kstep; const char* b3 = b2 + kstep;
;             if (last && has_next) S.a_ready(nxt);
;             if constexpr (SP2) {
;             PG8_LDB(B0, 0, 0); PG8_LDB(B1, 0, 1); PG8_SCHED; PG8_LDA(At, 0, 0); PG8_STAGE(PG8_SA(1, 1), a1 + hstepA, voffA);
;             PG8_WAIT_V(8); PG8_WAIT_L(0); PG8_BAR; PG8_MMA(0, 0, At, B0); PG8_MMA(0, 1, At, B1); PG8_BAR; PG8_SCHED;
;             PG8_LDA(At, 0, 1); PG8_STAGE(PG8_SB(0, 0), b2, voffB); PG8_STAGE(PG8_SB(0, 1), b2 + hstepB, voffB); PG8_STAGE(PG8_SA(0, 0), a2, voffA);
;             PG8_WAIT_V(8); PG8_WAIT_L(0); PG8_BAR; PG8_MMA(1, 0, At, B0); PG8_MMA(1, 1, At, B1); PG8_BAR; PG8_SCHED;
.LBB0_318:
	s_add_u32 s8, s20, 0x100
	s_addc_u32 s9, s21, 0
	s_add_i32 s53, 0, 0x10000
	s_cmpk_eq_i32 s52, 0x54
	s_cselect_b32 s25, s17, s9
	s_cselect_b32 s24, s16, s8
	s_cselect_b32 s23, s11, s51
	s_cselect_b32 s22, s10, s50
	s_add_i32 s54, 0, 0x14000
	v_add_u32_e32 v114, s53, v249
	v_add_u32_e32 v150, s54, v249
	ds_read_b128 v[82:85], v114
	ds_read_b128 v[94:97], v114 offset:1024
	ds_read_b128 v[106:109], v114 offset:2048
	ds_read_b128 v[114:117], v114 offset:3072
	ds_read_b128 v[130:133], v150
	ds_read_b128 v[134:137], v150 offset:1024
	ds_read_b128 v[146:149], v150 offset:2048
	ds_read_b128 v[150:153], v150 offset:3072
	v_lshl_add_u64 v[206:207], s[20:21], 0, v[204:205]
	s_add_i32 m0, s36, 0xc000
	ds_read_b128 v[154:157], v251
	ds_read_b128 v[166:169], v251 offset:1024
	ds_read_b128 v[170:173], v251 offset:2048
	ds_read_b128 v[174:177], v251 offset:3072
	ds_read_b128 v[178:181], v251 offset:4096
	ds_read_b128 v[182:185], v251 offset:5120
	ds_read_b128 v[186:189], v251 offset:6144
	ds_read_b128 v[194:197], v251 offset:7168
	global_load_lds_dwordx4 v[206:207], off
	v_lshl_add_u64 v[206:207], s[20:21], 0, v[202:203]
	s_add_i32 m0, s36, 0xe000
	s_nop 0
	global_load_lds_dwordx4 v[206:207], off
	s_waitcnt vmcnt(8)
	s_waitcnt lgkmcnt(0)
	s_barrier
	s_setprio 1
	s_waitcnt lgkmcnt(0)
	v_mfma_f32_16x16x32_bf16 v[162:165], v[82:85], v[154:157], v[162:165]
	v_mfma_f32_16x16x32_bf16 v[158:161], v[106:109], v[154:157], v[158:161]
	v_mfma_f32_16x16x32_bf16 v[126:129], v[82:85], v[170:173], v[126:129]
	v_mfma_f32_16x16x32_bf16 v[122:125], v[106:109], v[170:173], v[122:125]
	v_mfma_f32_16x16x32_bf16 v[102:105], v[82:85], v[178:181], v[102:105]
	v_mfma_f32_16x16x32_bf16 v[98:101], v[106:109], v[178:181], v[98:101]
	v_mfma_f32_16x16x32_bf16 v[78:81], v[82:85], v[186:189], v[78:81]
	v_mfma_f32_16x16x32_bf16 v[74:77], v[106:109], v[186:189], v[74:77]
	v_mfma_f32_16x16x32_bf16 v[162:165], v[94:97], v[166:169], v[162:165]
	v_mfma_f32_16x16x32_bf16 v[158:161], v[114:117], v[166:169], v[158:161]
	v_mfma_f32_16x16x32_bf16 v[126:129], v[94:97], v[174:177], v[126:129]
	v_mfma_f32_16x16x32_bf16 v[122:125], v[114:117], v[174:177], v[122:125]
	v_mfma_f32_16x16x32_bf16 v[102:105], v[94:97], v[182:185], v[102:105]
	v_mfma_f32_16x16x32_bf16 v[98:101], v[114:117], v[182:185], v[98:101]
	v_mfma_f32_16x16x32_bf16 v[78:81], v[94:97], v[194:197], v[78:81]
	v_mfma_f32_16x16x32_bf16 v[74:77], v[114:117], v[194:197], v[74:77]
	s_setprio 0
	s_setprio 1
	v_mfma_f32_16x16x32_bf16 v[142:145], v[130:133], v[154:157], v[142:145]
	v_mfma_f32_16x16x32_bf16 v[138:141], v[146:149], v[154:157], v[138:141]
	v_mfma_f32_16x16x32_bf16 v[118:121], v[130:133], v[170:173], v[118:121]
	v_mfma_f32_16x16x32_bf16 v[110:113], v[146:149], v[170:173], v[110:113]
	v_mfma_f32_16x16x32_bf16 v[90:93], v[130:133], v[178:181], v[90:93]
	v_mfma_f32_16x16x32_bf16 v[86:89], v[146:149], v[178:181], v[86:89]
	v_mfma_f32_16x16x32_bf16 v[70:73], v[130:133], v[186:189], v[70:73]
	v_mfma_f32_16x16x32_bf16 v[66:69], v[146:149], v[186:189], v[66:69]
	v_mfma_f32_16x16x32_bf16 v[142:145], v[134:137], v[166:169], v[142:145]
	v_mfma_f32_16x16x32_bf16 v[138:141], v[150:153], v[166:169], v[138:141]
	v_mfma_f32_16x16x32_bf16 v[118:121], v[134:137], v[174:177], v[118:121]
	v_mfma_f32_16x16x32_bf16 v[110:113], v[150:153], v[174:177], v[110:113]
	v_mfma_f32_16x16x32_bf16 v[90:93], v[134:137], v[182:185], v[90:93]
	v_mfma_f32_16x16x32_bf16 v[86:89], v[150:153], v[182:185], v[86:89]
	v_mfma_f32_16x16x32_bf16 v[70:73], v[134:137], v[194:197], v[70:73]
	v_mfma_f32_16x16x32_bf16 v[66:69], v[150:153], v[194:197], v[66:69]
	s_setprio 0
	s_barrier
	s_add_i32 s20, s53, s35
	v_lshl_add_u64 v[206:207], s[22:23], 0, v[0:1]
	s_mov_b32 m0, s20
	ds_read_b128 v[154:157], v251 offset:16384
	ds_read_b128 v[166:169], v251 offset:17408
	ds_read_b128 v[170:173], v251 offset:18432
	ds_read_b128 v[174:177], v251 offset:19456
	ds_read_b128 v[178:181], v251 offset:20480
	ds_read_b128 v[182:185], v251 offset:21504
	ds_read_b128 v[186:189], v251 offset:22528
	ds_read_b128 v[194:197], v251 offset:23552
	global_load_lds_dwordx4 v[206:207], off
	s_add_i32 m0, s20, 0x2000
	s_add_u32 s20, s22, 0x58000
	v_lshl_add_u64 v[208:209], s[22:23], 0, v[198:199]
	s_addc_u32 s21, s23, 0
	s_add_i32 s53, s54, s35
	global_load_lds_dwordx4 v[208:209], off
	v_lshl_add_u64 v[210:211], s[20:21], 0, v[0:1]
	s_mov_b32 m0, s53
	v_lshl_add_u64 v[212:213], s[24:25], 0, v[192:193]
	global_load_lds_dwordx4 v[210:211], off
	v_lshl_add_u64 v[210:211], s[20:21], 0, v[198:199]
	s_add_i32 m0, s53, 0x2000
	s_nop 0
	global_load_lds_dwordx4 v[210:211], off
	v_lshl_add_u64 v[210:211], s[24:25], 0, v[190:191]
	s_mov_b32 m0, s36
	s_nop 0
	global_load_lds_dwordx4 v[210:211], off
	s_mov_b32 m0, s37
	s_nop 0
	global_load_lds_dwordx4 v[212:213], off
	s_waitcnt vmcnt(8)
	s_waitcnt lgkmcnt(0)
	s_barrier
; #define PG8_STAGE(bufoff, gbase, voff) do { _Pragma("unroll") for (int _i = 0; _i < 2; ++_i) \
;         __builtin_amdgcn_global_load_lds((const unsigned*)((const char*)(gbase) + (voff)[_i]), (LAS unsigned*)(lds + (bufoff) + ldsw + _i * 8192), 16, 0, 0); } while (0)
; #define PG8_LDA(dst, b, h) do { _Pragma("unroll") for (int m = 0; m < 4; ++m) _Pragma("unroll") for (int k = 0; k < 2; ++k) dst[m][k] = *(const LAS bf16x8*)(lds + PG8_SA(b, h) + aoff + m * 2048 + k * 1024); } while (0)
; #define PG8_LDB(dst, b, h) do { _Pragma("unroll") for (int n = 0; n < 2; ++n) _Pragma("unroll") for (int k = 0; k < 2; ++k) dst[n][k] = *(const LAS bf16x8*)(lds + PG8_SB(b, h) + boff + n * 2048 + k * 1024); } while (0)
; #define PG8_MMA(ai, bj, At, Bt) do { __builtin_amdgcn_s_setprio(1); _Pragma("unroll") for (int m = 0; m < 4; ++m) _Pragma("unroll") for (int n = 0; n < 2; ++n) _Pragma("unroll") for (int k = 0; k < 2; ++k) \
;         acc[ai][bj][m][n] = __builtin_amdgcn_mfma_f32_16x16x32_bf16(Bt[n][k], At[m][k], acc[ai][bj][m][n], 0, 0, 0); __builtin_amdgcn_s_setprio(0); } while (0)
; #define PG8_WAIT_V(n) asm volatile("s_waitcnt vmcnt(" #n ")" ::: "memory")
; #define PG8_WAIT_L(n) asm volatile("s_waitcnt lgkmcnt(" #n ")" ::: "memory")
; #define PG8_BAR __builtin_amdgcn_s_barrier()
; #define PG8_SCHED __builtin_amdgcn_sched_barrier(0)
; template <class Epi, class Sched, int KC, bool ALIGN_EPI = false, bool SP2 = false, bool ATILED = false>
; __device__ __forceinline__ void gemm_phase(LAS unsigned char* lds, const Gemm g, const Sched& S, const Epi& E, int wave_s) {
;     ...
;             PG8_WAIT_V(8); PG8_WAIT_L(0); PG8_BAR; PG8_MMA(1, 0, At, B0); PG8_MMA(1, 1, At, B1); PG8_BAR; PG8_SCHED;
;             PG8_LDB(B0, 1, 0); PG8_LDB(B1, 1, 1); PG8_SCHED; PG8_LDA(At, 1, 0); PG8_STAGE(PG8_SA(0, 1), a2 + hstepA, voffA);
;             PG8_WAIT_V(8); PG8_WAIT_L(0); PG8_BAR; PG8_MMA(0, 0, At, B0); PG8_MMA(0, 1, At, B1); PG8_BAR; PG8_SCHED;
	s_setprio 1
	s_waitcnt lgkmcnt(0)
	v_mfma_f32_16x16x32_bf16 v[62:65], v[82:85], v[154:157], v[62:65]
	v_mfma_f32_16x16x32_bf16 v[58:61], v[106:109], v[154:157], v[58:61]
	v_mfma_f32_16x16x32_bf16 v[46:49], v[82:85], v[170:173], v[46:49]
	v_mfma_f32_16x16x32_bf16 v[42:45], v[106:109], v[170:173], v[42:45]
	v_mfma_f32_16x16x32_bf16 v[30:33], v[82:85], v[178:181], v[30:33]
	v_mfma_f32_16x16x32_bf16 v[26:29], v[106:109], v[178:181], v[26:29]
	v_mfma_f32_16x16x32_bf16 v[14:17], v[82:85], v[186:189], v[14:17]
	v_mfma_f32_16x16x32_bf16 v[10:13], v[106:109], v[186:189], v[10:13]
	v_mfma_f32_16x16x32_bf16 v[62:65], v[94:97], v[166:169], v[62:65]
	v_mfma_f32_16x16x32_bf16 v[58:61], v[114:117], v[166:169], v[58:61]
	v_mfma_f32_16x16x32_bf16 v[46:49], v[94:97], v[174:177], v[46:49]
	v_mfma_f32_16x16x32_bf16 v[42:45], v[114:117], v[174:177], v[42:45]
	v_mfma_f32_16x16x32_bf16 v[30:33], v[94:97], v[182:185], v[30:33]
	v_mfma_f32_16x16x32_bf16 v[26:29], v[114:117], v[182:185], v[26:29]
	v_mfma_f32_16x16x32_bf16 v[14:17], v[94:97], v[194:197], v[14:17]
	v_mfma_f32_16x16x32_bf16 v[10:13], v[114:117], v[194:197], v[10:13]
	s_setprio 0
	s_setprio 1
	v_mfma_f32_16x16x32_bf16 v[54:57], v[130:133], v[154:157], v[54:57]
	v_mfma_f32_16x16x32_bf16 v[50:53], v[146:149], v[154:157], v[50:53]
	v_mfma_f32_16x16x32_bf16 v[38:41], v[130:133], v[170:173], v[38:41]
	v_mfma_f32_16x16x32_bf16 v[34:37], v[146:149], v[170:173], v[34:37]
	v_mfma_f32_16x16x32_bf16 v[22:25], v[130:133], v[178:181], v[22:25]
	v_mfma_f32_16x16x32_bf16 v[18:21], v[146:149], v[178:181], v[18:21]
	v_mfma_f32_16x16x32_bf16 v[6:9], v[130:133], v[186:189], v[6:9]
	v_mfma_f32_16x16x32_bf16 v[2:5], v[146:149], v[186:189], v[2:5]
	v_mfma_f32_16x16x32_bf16 v[54:57], v[134:137], v[166:169], v[54:57]
	v_mfma_f32_16x16x32_bf16 v[50:53], v[150:153], v[166:169], v[50:53]
	v_mfma_f32_16x16x32_bf16 v[38:41], v[134:137], v[174:177], v[38:41]
	v_mfma_f32_16x16x32_bf16 v[34:37], v[150:153], v[174:177], v[34:37]
	v_mfma_f32_16x16x32_bf16 v[22:25], v[134:137], v[182:185], v[22:25]
	v_mfma_f32_16x16x32_bf16 v[18:21], v[150:153], v[182:185], v[18:21]
	v_mfma_f32_16x16x32_bf16 v[6:9], v[134:137], v[194:197], v[6:9]
	v_mfma_f32_16x16x32_bf16 v[2:5], v[150:153], v[194:197], v[2:5]
	s_setprio 0
	s_barrier
	s_add_i32 s53, 0, 0x18000
	s_add_i32 s54, 0, 0x1c000
	v_add_u32_e32 v114, s53, v249
	v_add_u32_e32 v150, s54, v249
	ds_read_b128 v[82:85], v114
	ds_read_b128 v[94:97], v114 offset:1024
	ds_read_b128 v[106:109], v114 offset:2048
	ds_read_b128 v[114:117], v114 offset:3072
	ds_read_b128 v[130:133], v150
	ds_read_b128 v[134:137], v150 offset:1024
	ds_read_b128 v[146:149], v150 offset:2048
	ds_read_b128 v[150:153], v150 offset:3072
	s_add_u32 s20, s24, 0x160000
	s_addc_u32 s21, s25, 0
	s_mov_b32 m0, s38
	v_lshl_add_u64 v[214:215], s[20:21], 0, v[190:191]
	ds_read_b128 v[154:157], v251 offset:32768
	ds_read_b128 v[166:169], v251 offset:33792
	ds_read_b128 v[170:173], v251 offset:34816
	ds_read_b128 v[174:177], v251 offset:35840
	ds_read_b128 v[178:181], v251 offset:36864
	ds_read_b128 v[182:185], v251 offset:37888
	ds_read_b128 v[186:189], v251 offset:38912
	ds_read_b128 v[194:197], v251 offset:39936
	global_load_lds_dwordx4 v[214:215], off
	v_lshl_add_u64 v[214:215], s[20:21], 0, v[192:193]
	s_mov_b32 m0, s39
	s_nop 0
	global_load_lds_dwordx4 v[214:215], off
	s_waitcnt vmcnt(8)
	s_waitcnt lgkmcnt(0)
	s_barrier
	s_setprio 1
	s_waitcnt lgkmcnt(0)
	v_mfma_f32_16x16x32_bf16 v[162:165], v[82:85], v[154:157], v[162:165]
	v_mfma_f32_16x16x32_bf16 v[158:161], v[106:109], v[154:157], v[158:161]
	v_mfma_f32_16x16x32_bf16 v[126:129], v[82:85], v[170:173], v[126:129]
	v_mfma_f32_16x16x32_bf16 v[122:125], v[106:109], v[170:173], v[122:125]
	v_mfma_f32_16x16x32_bf16 v[102:105], v[82:85], v[178:181], v[102:105]
	v_mfma_f32_16x16x32_bf16 v[98:101], v[106:109], v[178:181], v[98:101]
	v_mfma_f32_16x16x32_bf16 v[78:81], v[82:85], v[186:189], v[78:81]
	v_mfma_f32_16x16x32_bf16 v[74:77], v[106:109], v[186:189], v[74:77]
	v_mfma_f32_16x16x32_bf16 v[162:165], v[94:97], v[166:169], v[162:165]
	v_mfma_f32_16x16x32_bf16 v[158:161], v[114:117], v[166:169], v[158:161]
	v_mfma_f32_16x16x32_bf16 v[126:129], v[94:97], v[174:177], v[126:129]
	v_mfma_f32_16x16x32_bf16 v[122:125], v[114:117], v[174:177], v[122:125]
	v_mfma_f32_16x16x32_bf16 v[102:105], v[94:97], v[182:185], v[102:105]
	v_mfma_f32_16x16x32_bf16 v[98:101], v[114:117], v[182:185], v[98:101]
	v_mfma_f32_16x16x32_bf16 v[78:81], v[94:97], v[194:197], v[78:81]
	v_mfma_f32_16x16x32_bf16 v[74:77], v[114:117], v[194:197], v[74:77]
	s_setprio 0
	s_setprio 1
	v_mfma_f32_16x16x32_bf16 v[142:145], v[130:133], v[154:157], v[142:145]
	v_mfma_f32_16x16x32_bf16 v[138:141], v[146:149], v[154:157], v[138:141]
	v_mfma_f32_16x16x32_bf16 v[118:121], v[130:133], v[170:173], v[118:121]
	v_mfma_f32_16x16x32_bf16 v[110:113], v[146:149], v[170:173], v[110:113]
	v_mfma_f32_16x16x32_bf16 v[90:93], v[130:133], v[178:181], v[90:93]
	v_mfma_f32_16x16x32_bf16 v[86:89], v[146:149], v[178:181], v[86:89]
	v_mfma_f32_16x16x32_bf16 v[70:73], v[130:133], v[186:189], v[70:73]
	v_mfma_f32_16x16x32_bf16 v[66:69], v[146:149], v[186:189], v[66:69]
	v_mfma_f32_16x16x32_bf16 v[142:145], v[134:137], v[166:169], v[142:145]
	v_mfma_f32_16x16x32_bf16 v[138:141], v[150:153], v[166:169], v[138:141]
	v_mfma_f32_16x16x32_bf16 v[118:121], v[134:137], v[174:177], v[118:121]
	v_mfma_f32_16x16x32_bf16 v[110:113], v[150:153], v[174:177], v[110:113]
	v_mfma_f32_16x16x32_bf16 v[90:93], v[134:137], v[182:185], v[90:93]
	v_mfma_f32_16x16x32_bf16 v[86:89], v[150:153], v[182:185], v[86:89]
	v_mfma_f32_16x16x32_bf16 v[70:73], v[134:137], v[194:197], v[70:73]
	v_mfma_f32_16x16x32_bf16 v[66:69], v[150:153], v[194:197], v[66:69]
	s_setprio 0
	s_barrier
; #define PG8_STAGE(bufoff, gbase, voff) do { _Pragma("unroll") for (int _i = 0; _i < 2; ++_i) \
;         __builtin_amdgcn_global_load_lds((const unsigned*)((const char*)(gbase) + (voff)[_i]), (LAS unsigned*)(lds + (bufoff) + ldsw + _i * 8192), 16, 0, 0); } while (0)
; #define PG8_LDA(dst, b, h) do { _Pragma("unroll") for (int m = 0; m < 4; ++m) _Pragma("unroll") for (int k = 0; k < 2; ++k) dst[m][k] = *(const LAS bf16x8*)(lds + PG8_SA(b, h) + aoff + m * 2048 + k * 1024); } while (0)
; #define PG8_BAR __builtin_amdgcn_s_barrier()
; template <class Epi, class Sched, int KC, bool ALIGN_EPI = false, bool SP2 = false, bool ATILED = false>
; __device__ __forceinline__ void gemm_phase(LAS unsigned char* lds, const Gemm g, const Sched& S, const Epi& E, int wave_s) {
;     ...
;             PG8_LDA(At, 1, 1); PG8_STAGE(PG8_SB(1, 0), b3, voffB); PG8_STAGE(PG8_SB(1, 1), b3 + hstepB, voffB); PG8_STAGE(PG8_SA(1, 0), a3, voffA);
;             PG8_WAIT_V(8); PG8_WAIT_L(0); PG8_BAR; PG8_MMA(1, 0, At, B0); PG8_MMA(1, 1, At, B1); PG8_BAR; PG8_SCHED;
;             } else {
;             PG8_LDB(B0, 0, 0); PG8_SCHED; PG8_LDA(At, 0, 0); PG8_STAGE(PG8_SA(1, 1), a1 + hstepA, voffA);
;             PG8_WAIT_L(8); PG8_BAR; PG8_WAIT_L(0); PG8_MMA(0, 0, At, B0); PG8_BAR; PG8_SCHED;
;             PG8_LDB(B1, 0, 1); PG8_STAGE(PG8_SB(0, 0), b2, voffB);
;             PG8_BAR; PG8_WAIT_L(0); PG8_MMA(0, 1, At, B1); PG8_BAR;
;             PG8_LDA(At, 0, 1); PG8_STAGE(PG8_SA(0, 0), a2, voffA);
;             PG8_BAR; PG8_WAIT_L(0); PG8_MMA(1, 0, At, B0); PG8_BAR; PG8_SCHED;
;             PG8_STAGE(PG8_SB(0, 1), b2 + hstepB, voffB);
;             PG8_WAIT_V(6); PG8_BAR; PG8_MMA(1, 1, At, B1); PG8_BAR;
;             PG8_LDB(B0, 1, 0); PG8_SCHED; PG8_LDA(At, 1, 0); PG8_STAGE(PG8_SA(0, 1), a2 + hstepA, voffA);
;             PG8_WAIT_L(8); PG8_BAR; PG8_WAIT_L(0); PG8_MMA(0, 0, At, B0); PG8_BAR; PG8_SCHED;
;             PG8_LDB(B1, 1, 1); PG8_STAGE(PG8_SB(1, 0), b3, voffB);
;             PG8_BAR; PG8_WAIT_L(0); PG8_MMA(0, 1, At, B1); PG8_BAR;
;             PG8_LDA(At, 1, 1); PG8_STAGE(PG8_SA(1, 0), a3, voffA);
;             PG8_BAR; PG8_WAIT_L(0); PG8_MMA(1, 0, At, B0); PG8_BAR; PG8_SCHED;
;             PG8_STAGE(PG8_SB(1, 1), b3 + hstepB, voffB);
;             PG8_WAIT_V(6); PG8_BAR; PG8_MMA(1, 1, At, B1); PG8_BAR;
;             }
;         }
;         if constexpr (ALIGN_EPI) { if (wr == 0) PG8_BAR; }
	s_add_i32 s20, s53, s35
	v_lshl_add_u64 v[206:207], v[206:207], 0, s[96:97]
	s_mov_b32 m0, s20
	ds_read_b128 v[154:157], v251 offset:49152
	ds_read_b128 v[166:169], v251 offset:50176
	ds_read_b128 v[170:173], v251 offset:51200
	ds_read_b128 v[174:177], v251 offset:52224
	ds_read_b128 v[178:181], v251 offset:53248
	ds_read_b128 v[182:185], v251 offset:54272
	ds_read_b128 v[186:189], v251 offset:55296
	ds_read_b128 v[194:197], v251 offset:56320
	global_load_lds_dwordx4 v[206:207], off
	s_add_i32 m0, s20, 0x2000
	s_add_u32 s20, s22, 0x58080
	v_lshl_add_u64 v[206:207], v[208:209], 0, s[96:97]
	s_addc_u32 s21, s23, 0
	s_add_i32 s22, s54, s35
	global_load_lds_dwordx4 v[206:207], off
	v_lshl_add_u64 v[206:207], s[20:21], 0, v[0:1]
	s_mov_b32 m0, s22
	s_nop 0
	global_load_lds_dwordx4 v[206:207], off
	v_lshl_add_u64 v[206:207], s[20:21], 0, v[198:199]
	s_add_i32 m0, s22, 0x2000
	s_nop 0
	global_load_lds_dwordx4 v[206:207], off
	v_lshl_add_u64 v[206:207], v[210:211], 0, s[96:97]
	s_mov_b32 m0, s43
	s_nop 0
	global_load_lds_dwordx4 v[206:207], off
	v_lshl_add_u64 v[206:207], v[212:213], 0, s[96:97]
	s_mov_b32 m0, s44
	s_nop 0
	global_load_lds_dwordx4 v[206:207], off
	s_waitcnt vmcnt(8)
	s_waitcnt lgkmcnt(0)
	s_barrier
	s_setprio 1
	s_waitcnt lgkmcnt(0)
	v_mfma_f32_16x16x32_bf16 v[62:65], v[82:85], v[154:157], v[62:65]
	v_mfma_f32_16x16x32_bf16 v[58:61], v[106:109], v[154:157], v[58:61]
	v_mfma_f32_16x16x32_bf16 v[46:49], v[82:85], v[170:173], v[46:49]
	v_mfma_f32_16x16x32_bf16 v[42:45], v[106:109], v[170:173], v[42:45]
	v_mfma_f32_16x16x32_bf16 v[30:33], v[82:85], v[178:181], v[30:33]
	v_mfma_f32_16x16x32_bf16 v[26:29], v[106:109], v[178:181], v[26:29]
	v_mfma_f32_16x16x32_bf16 v[14:17], v[82:85], v[186:189], v[14:17]
	v_mfma_f32_16x16x32_bf16 v[10:13], v[106:109], v[186:189], v[10:13]
	v_mfma_f32_16x16x32_bf16 v[62:65], v[94:97], v[166:169], v[62:65]
	v_mfma_f32_16x16x32_bf16 v[58:61], v[114:117], v[166:169], v[58:61]
	v_mfma_f32_16x16x32_bf16 v[46:49], v[94:97], v[174:177], v[46:49]
	v_mfma_f32_16x16x32_bf16 v[42:45], v[114:117], v[174:177], v[42:45]
	v_mfma_f32_16x16x32_bf16 v[30:33], v[94:97], v[182:185], v[30:33]
	v_mfma_f32_16x16x32_bf16 v[26:29], v[114:117], v[182:185], v[26:29]
	v_mfma_f32_16x16x32_bf16 v[14:17], v[94:97], v[194:197], v[14:17]
	v_mfma_f32_16x16x32_bf16 v[10:13], v[114:117], v[194:197], v[10:13]
	s_setprio 0
	s_setprio 1
	v_mfma_f32_16x16x32_bf16 v[54:57], v[130:133], v[154:157], v[54:57]
	v_mfma_f32_16x16x32_bf16 v[50:53], v[146:149], v[154:157], v[50:53]
	v_mfma_f32_16x16x32_bf16 v[38:41], v[130:133], v[170:173], v[38:41]
	v_mfma_f32_16x16x32_bf16 v[34:37], v[146:149], v[170:173], v[34:37]
	v_mfma_f32_16x16x32_bf16 v[22:25], v[130:133], v[178:181], v[22:25]
	v_mfma_f32_16x16x32_bf16 v[18:21], v[146:149], v[178:181], v[18:21]
	v_mfma_f32_16x16x32_bf16 v[6:9], v[130:133], v[186:189], v[6:9]
	v_mfma_f32_16x16x32_bf16 v[2:5], v[146:149], v[186:189], v[2:5]
	v_mfma_f32_16x16x32_bf16 v[54:57], v[134:137], v[166:169], v[54:57]
	v_mfma_f32_16x16x32_bf16 v[50:53], v[150:153], v[166:169], v[50:53]
	v_mfma_f32_16x16x32_bf16 v[38:41], v[134:137], v[174:177], v[38:41]
	v_mfma_f32_16x16x32_bf16 v[34:37], v[150:153], v[174:177], v[34:37]
	v_mfma_f32_16x16x32_bf16 v[22:25], v[134:137], v[182:185], v[22:25]
	v_mfma_f32_16x16x32_bf16 v[18:21], v[150:153], v[182:185], v[18:21]
	v_mfma_f32_16x16x32_bf16 v[6:9], v[134:137], v[194:197], v[6:9]
	v_mfma_f32_16x16x32_bf16 v[2:5], v[150:153], v[194:197], v[2:5]
	s_setprio 0
	s_barrier
	s_add_i32 s52, s52, 2
	s_add_u32 s50, s50, 0x100
	s_addc_u32 s51, s51, 0
	s_cmpk_gt_u32 s52, 0x55
	s_mov_b64 s[20:21], s[8:9]
	s_cbranch_scc0 .LBB0_318
	s_cmpk_gt_u32 s28, 0xff
	s_cbranch_scc1 .Lffo_epi
	s_barrier
; #define GAS __attribute__((address_space(1)))
; DI unsigned cvtpk(float lo, float hi) { unsigned r; asm volatile("v_cvt_pk_bf16_f32 %0, %1, %2" : "=v"(r) : "v"(lo), "v"(hi)); return r; }
;     DI void operator()(const f32x4 (&acc)[2][2][4][2], const Unit& u, int wr, int wc, int fr, int fq) const {
;         const int row0 = u.pm * BM + wr * 64 + fr, col0 = u.pn * BM + wc * 64 + 8 * fq;
;         const size_t hbase = (size_t)u.pn * ((size_t)M * 256) + wc * 64 + 8 * fq;
;         u32x4 H[2][4][2];
; #pragma unroll
;         for (int ai = 0; ai < 2; ++ai)
; #pragma unroll
;             for (int m = 0; m < 4; ++m)
; #pragma unroll
;                 for (int bj = 0; bj < 2; ++bj) H[ai][m][bj] = *(const GAS u32x4*)(hi + hbase + (size_t)(row0 + ai * HALF + m * 16) * 256 + bj * 32);
;         asm volatile("" ::: "memory");
; #pragma unroll
;         for (int ai = 0; ai < 2; ++ai) {
; #pragma unroll
;             for (int m = 0; m < 4; ++m) {
;                 const int r = row0 + ai * HALF + m * 16; const size_t off = (size_t)r * DM + col0; float ss = 0.f;
; #pragma unroll
;                 for (int bj = 0; bj < 2; ++bj) {
;                     const u32x4 h = H[ai][m][bj];
;                     const f32x4 a0 = acc[ai][bj][m][0], a1 = acc[ai][bj][m][1];
;                     float v[8];
;                     v[0] = bflo(h.x) + a0[0] * scale; v[1] = bfhi(h.x) + a0[1] * scale;
;                     v[2] = bflo(h.y) + a0[2] * scale; v[3] = bfhi(h.y) + a0[3] * scale;
;                     v[4] = bflo(h.z) + a1[0] * scale; v[5] = bfhi(h.z) + a1[1] * scale;
;                     v[6] = bflo(h.w) + a1[2] * scale; v[7] = bfhi(h.w) + a1[3] * scale;
; #pragma unroll
;                     for (int e = 0; e < 8; ++e) ss += v[e] * v[e];
;                     u32x4 nh;
;                     nh.x = cvtpk(v[0], v[1]); nh.y = cvtpk(v[2], v[3]); nh.z = cvtpk(v[4], v[5]); nh.w = cvtpk(v[6], v[7]);
;                     *(GAS u32x4*)(hi + hbase + (size_t)r * 256 + bj * 32) = nh;
;                     if (out) { *(GAS f32x4*)(out + off + bj * 32) = (f32x4){v[0], v[1], v[2], v[3]}; *(GAS f32x4*)(out + off + bj * 32 + 4) = (f32x4){v[4], v[5], v[6], v[7]}; }
.Lffo_epi:
	v_lshl_add_u32 v206, s19, 8, v248
	s_ashr_i32 s19, s18, 31
	s_lshl_b64 s[8:9], s[18:19], 23
	v_ashrrev_i32_e32 v207, 31, v206
	v_or_b32_e32 v236, 16, v206
	v_lshl_add_u64 v[82:83], v[200:201], 0, s[8:9]
	v_lshlrev_b64 v[84:85], 9, v[206:207]
	v_ashrrev_i32_e32 v237, 31, v236
	v_or_b32_e32 v232, 32, v206
	v_lshl_add_u64 v[238:239], v[82:83], 0, v[84:85]
	v_lshlrev_b64 v[84:85], 9, v[236:237]
	v_ashrrev_i32_e32 v233, 31, v232
	v_or_b32_e32 v228, 48, v206
	v_lshl_add_u64 v[234:235], v[82:83], 0, v[84:85]
	v_lshlrev_b64 v[84:85], 9, v[232:233]
	v_ashrrev_i32_e32 v229, 31, v228
	v_add_u32_e32 v224, 0x80, v206
	v_lshl_add_u64 v[230:231], v[82:83], 0, v[84:85]
	v_lshlrev_b64 v[84:85], 9, v[228:229]
	v_ashrrev_i32_e32 v225, 31, v224
	v_add_u32_e32 v220, 0x90, v206
	global_load_dwordx4 v[194:197], v[238:239], off
	global_load_dwordx4 v[186:189], v[238:239], off offset:64
	v_lshl_add_u64 v[226:227], v[82:83], 0, v[84:85]
	v_lshlrev_b64 v[84:85], 9, v[224:225]
	v_ashrrev_i32_e32 v221, 31, v220
	v_add_u32_e32 v216, 0xa0, v206
	v_lshl_add_u64 v[222:223], v[82:83], 0, v[84:85]
	v_lshlrev_b64 v[84:85], 9, v[220:221]
	v_ashrrev_i32_e32 v217, 31, v216
	v_add_u32_e32 v210, 0xb0, v206
	v_lshl_add_u64 v[218:219], v[82:83], 0, v[84:85]
	v_lshlrev_b64 v[84:85], 9, v[216:217]
	v_ashrrev_i32_e32 v211, 31, v210
	v_lshl_add_u64 v[214:215], v[82:83], 0, v[84:85]
	v_lshlrev_b64 v[84:85], 9, v[210:211]
	v_lshl_add_u64 v[208:209], v[82:83], 0, v[84:85]
	global_load_dwordx4 v[182:185], v[234:235], off
	global_load_dwordx4 v[178:181], v[234:235], off offset:64
	global_load_dwordx4 v[174:177], v[230:231], off
	global_load_dwordx4 v[170:173], v[230:231], off offset:64
	global_load_dwordx4 v[166:169], v[226:227], off
	global_load_dwordx4 v[154:157], v[226:227], off offset:64
	global_load_dwordx4 v[150:153], v[222:223], off
	global_load_dwordx4 v[146:149], v[222:223], off offset:64
	global_load_dwordx4 v[134:137], v[218:219], off
	global_load_dwordx4 v[130:133], v[218:219], off offset:64
	global_load_dwordx4 v[114:117], v[214:215], off
	global_load_dwordx4 v[106:109], v[214:215], off offset:64
	global_load_dwordx4 v[94:97], v[208:209], off
	global_load_dwordx4 v[82:85], v[208:209], off offset:64
	v_lshl_or_b32 v212, s18, 8, v250
	v_ashrrev_i32_e32 v213, 31, v212
	v_lshlrev_b64 v[240:241], 11, v[206:207]
	v_lshl_add_u64 v[240:241], v[240:241], 0, v[212:213]
	s_andn2_b64 vcc, exec, s[14:15]
	v_lshl_add_u64 v[240:241], v[240:241], 2, s[12:13]
	s_waitcnt vmcnt(0)
	v_lshlrev_b32_e32 v252, 16, v194
	v_and_b32_e32 v253, 0xffff0000, v194
	v_lshlrev_b32_e32 v194, 16, v195
	v_and_b32_e32 v195, 0xffff0000, v195
	v_pk_fma_f32 v[164:165], v[164:165], 0.5, v[194:195] op_sel_hi:[1,0,1]
	v_lshlrev_b32_e32 v194, 16, v196
	v_and_b32_e32 v195, 0xffff0000, v196
	v_pk_fma_f32 v[158:159], v[158:159], 0.5, v[194:195] op_sel_hi:[1,0,1]
	v_lshlrev_b32_e32 v194, 16, v197
	v_and_b32_e32 v195, 0xffff0000, v197
	v_pk_fma_f32 v[162:163], v[162:163], 0.5, v[252:253] op_sel_hi:[1,0,1]
	v_pk_fma_f32 v[160:161], v[160:161], 0.5, v[194:195] op_sel_hi:[1,0,1]
	v_cvt_pk_bf16_f32 v194, v162, v163
	v_cvt_pk_bf16_f32 v195, v164, v165
	v_cvt_pk_bf16_f32 v196, v158, v159
	s_nop 0
	v_cvt_pk_bf16_f32 v197, v160, v161
	global_store_dwordx4 v[238:239], v[194:197], off
	s_nop 1
	v_cndmask_b32_e64 v194, 0, 1, s[14:15]
	v_cmp_ne_u32_e64 s[8:9], 1, v194
	s_cbranch_vccnz .LBB0_321
	global_store_dwordx4 v[240:241], v[162:165], off
	global_store_dwordx4 v[240:241], v[158:161], off offset:16

; #define PG8_WAIT_V(n) asm volatile("s_waitcnt vmcnt(" #n ")" ::: "memory")
; #define PG8_BAR __builtin_amdgcn_s_barrier()
; template <class Epi, class Sched, int KC, bool ALIGN_EPI = false, bool SP2 = false, bool ATILED = false>
; __device__ __forceinline__ void gemm_phase(LAS unsigned char* lds, const Gemm g, const Sched& S, const Epi& E, int wave_s) {
;     ...
;     PG8_WAIT_V(0);
;     if constexpr (!ALIGN_EPI) { if (wr == 0) PG8_BAR; }
;     PG8_BAR;
.LBB0_367:
	s_waitcnt vmcnt(0)
.LBB0_369:
	s_barrier

; #define PG8_BAR __builtin_amdgcn_s_barrier()
;     __host__ __device__ bool next(int i, Unit& u) const {
;         const long L = (long)i * G + c; if (L >= nwg) return false;
;         int wgid = (int)L; { const int q = nwg / NXCD, r = nwg % NXCD, xcd = wgid % NXCD, off = wgid / NXCD; wgid = (xcd < r ? xcd * (q + 1) : r * (q + 1) + (xcd - r) * q) + off; }
;         const int nig = WGM * nN, gid = wgid / nig, fm = gid * WGM, gsz = (nM - fm) < WGM ? (nM - fm) : WGM;
;         u.pm = fm + ((wgid % nig) % gsz); u.pn = (wgid % nig) / gsz; return true;
; template <class Epi, class Sched, int KC, bool ALIGN_EPI = false, bool SP2 = false, bool ATILED = false>
; __device__ __forceinline__ void gemm_phase(LAS unsigned char* lds, const Gemm g, const Sched& S, const Epi& E, int wave_s) {
;     ...
;         if (!has_next) break;
; #pragma unroll
;         for (int a = 0; a < 2; ++a)
; #pragma unroll
;             for (int b = 0; b < 2; ++b)
; #pragma unroll
;                 for (int m = 0; m < 4; ++m)
; #pragma unroll
;                     for (int n = 0; n < 2; ++n) acc[a][b][m][n] = (f32x4){0.f, 0.f, 0.f, 0.f};
;         cur = nxt; cA = nA; cB = nB; ++ui;
;         if constexpr (ALIGN_EPI) { if (wr == 1) PG8_BAR; }
.LBB0_1013:
	s_or_b64 exec, exec, s[16:17]
	s_and_b64 vcc, exec, s[6:7]
	s_mov_b32 s14, s2
	s_mov_b32 s16, s8
	s_mov_b64 s[18:19], s[12:13]
	s_mov_b64 s[20:21], s[10:11]
	s_cbranch_vccnz .LBB0_1038
	s_cmpk_lt_u32 s26, 0x100
	s_cbranch_scc1 .Lout_next
	s_barrier
.Lout_next:
.LBB0_1014:
	s_add_i32 s43, s43, 1
	s_mul_i32 s3, s43, s44
	s_mul_hi_u32 s6, s43, s24
	s_add_i32 s6, s6, s3
	s_mul_i32 s3, s43, s24
	s_add_u32 s10, s3, s25
	s_addc_u32 s11, s6, s45
	v_mov_b64_e32 v[2:3], 0x1ff
	v_cmp_gt_i64_e64 s[6:7], s[10:11], v[2:3]
	s_and_b64 vcc, exec, s[6:7]
	s_cbranch_vccnz .LBB0_1020
	s_ashr_i32 s2, s10, 31
	s_lshr_b32 s2, s2, 29
	s_add_i32 s8, s10, s2
	s_and_b32 s2, s8, -8
	s_sub_i32 s9, s10, s2
	s_cmp_gt_i32 s9, -1
	s_mov_b64 s[2:3], -1
	s_cbranch_scc0 .LBB0_1017
	s_lshl_b32 s12, s9, 6
	s_mov_b64 s[2:3], 0

; #define PG8_STAGE(bufoff, gbase, voff) do { _Pragma("unroll") for (int _i = 0; _i < 2; ++_i) \
;         __builtin_amdgcn_global_load_lds((const unsigned*)((const char*)(gbase) + (voff)[_i]), (LAS unsigned*)(lds + (bufoff) + ldsw + _i * 8192), 16, 0, 0); } while (0)
; #define PG8_LDA(dst, b, h) do { _Pragma("unroll") for (int m = 0; m < 4; ++m) _Pragma("unroll") for (int k = 0; k < 2; ++k) dst[m][k] = *(const LAS bf16x8*)(lds + PG8_SA(b, h) + aoff + m * 2048 + k * 1024); } while (0)
; #define PG8_LDB(dst, b, h) do { _Pragma("unroll") for (int n = 0; n < 2; ++n) _Pragma("unroll") for (int k = 0; k < 2; ++k) dst[n][k] = *(const LAS bf16x8*)(lds + PG8_SB(b, h) + boff + n * 2048 + k * 1024); } while (0)
; #define PG8_MMA(ai, bj, At, Bt) do { __builtin_amdgcn_s_setprio(1); _Pragma("unroll") for (int m = 0; m < 4; ++m) _Pragma("unroll") for (int n = 0; n < 2; ++n) _Pragma("unroll") for (int k = 0; k < 2; ++k) \
;         acc[ai][bj][m][n] = __builtin_amdgcn_mfma_f32_16x16x32_bf16(Bt[n][k], At[m][k], acc[ai][bj][m][n], 0, 0, 0); __builtin_amdgcn_s_setprio(0); } while (0)
; #define PG8_WAIT_V(n) asm volatile("s_waitcnt vmcnt(" #n ")" ::: "memory")
; #define PG8_BAR __builtin_amdgcn_s_barrier()
; template <class Epi, class Sched, int KC, bool ALIGN_EPI = false, bool SP2 = false, bool ATILED = false>
; __device__ __forceinline__ void gemm_phase(LAS unsigned char* lds, const Gemm g, const Sched& S, const Epi& E, int wave_s) {
;     ...
;         for (int t = 0; t < nt; t += 2) {
;             const bool last = (t == nt - 2);
;             const char* a1 = cA + PG8_AOFF(t + 1);
;             const char* a2 = last ? nA : cA + PG8_AOFF(t + 2); const char* b2 = last ? nB : cB + (size_t)(t + 2) * kstep;
;             const char* a3 = a2 + kstep; const char* b3 = b2 + kstep;
;             if (last && has_next) S.a_ready(nxt);
;             if constexpr (SP2) {
;             PG8_LDB(B0, 0, 0); PG8_LDB(B1, 0, 1); PG8_SCHED; PG8_LDA(At, 0, 0); PG8_STAGE(PG8_SA(1, 1), a1 + hstepA, voffA);
;             PG8_WAIT_V(8); PG8_WAIT_L(0); PG8_BAR; PG8_MMA(0, 0, At, B0); PG8_MMA(0, 1, At, B1); PG8_BAR; PG8_SCHED;
;             PG8_LDA(At, 0, 1); PG8_STAGE(PG8_SB(0, 0), b2, voffB); PG8_STAGE(PG8_SB(0, 1), b2 + hstepB, voffB); PG8_STAGE(PG8_SA(0, 0), a2, voffA);
;             PG8_WAIT_V(8); PG8_WAIT_L(0); PG8_BAR; PG8_MMA(1, 0, At, B0); PG8_MMA(1, 1, At, B1); PG8_BAR; PG8_SCHED;
.LBB0_1021:
	s_add_u32 s20, s18, 0xfff80080
	s_addc_u32 s21, s19, -1
	s_add_i32 s49, 0, 0x10000
	s_cmp_eq_u32 s48, 28
	s_cselect_b32 s23, s9, s21
	s_cselect_b32 s22, s15, s20
	s_cselect_b32 s21, s3, s47
	s_cselect_b32 s20, s17, s46
	s_add_i32 s52, 0, 0x14000
	v_add_u32_e32 v142, s49, v229
	v_add_u32_e32 v158, s52, v229
	ds_read_b128 v[130:133], v142
	ds_read_b128 v[134:137], v142 offset:1024
	ds_read_b128 v[138:141], v142 offset:2048
	ds_read_b128 v[142:145], v142 offset:3072
	ds_read_b128 v[146:149], v158
	ds_read_b128 v[150:153], v158 offset:1024
	ds_read_b128 v[154:157], v158 offset:2048
	ds_read_b128 v[158:161], v158 offset:3072
	v_lshl_add_u64 v[194:195], s[18:19], 0, v[208:209]
	s_add_i32 m0, s34, 0xc000
	ds_read_b128 v[162:165], v230
	ds_read_b128 v[166:169], v230 offset:1024
	ds_read_b128 v[170:173], v230 offset:2048
	ds_read_b128 v[174:177], v230 offset:3072
	ds_read_b128 v[178:181], v230 offset:4096
	ds_read_b128 v[182:185], v230 offset:5120
	ds_read_b128 v[186:189], v230 offset:6144
	ds_read_b128 v[190:193], v230 offset:7168
	global_load_lds_dwordx4 v[194:195], off
	v_lshl_add_u64 v[194:195], s[18:19], 0, v[206:207]
	s_add_i32 m0, s34, 0xe000
	s_nop 0
	global_load_lds_dwordx4 v[194:195], off
	s_waitcnt vmcnt(8)
	s_waitcnt lgkmcnt(0)
	s_barrier
	s_setprio 1
	s_waitcnt lgkmcnt(0)
	v_mfma_f32_16x16x32_bf16 v[126:129], v[130:133], v[162:165], v[126:129]
	v_mfma_f32_16x16x32_bf16 v[122:125], v[138:141], v[162:165], v[122:125]
	v_mfma_f32_16x16x32_bf16 v[110:113], v[130:133], v[170:173], v[110:113]
	v_mfma_f32_16x16x32_bf16 v[106:109], v[138:141], v[170:173], v[106:109]
	v_mfma_f32_16x16x32_bf16 v[94:97], v[130:133], v[178:181], v[94:97]
	v_mfma_f32_16x16x32_bf16 v[90:93], v[138:141], v[178:181], v[90:93]
	v_mfma_f32_16x16x32_bf16 v[78:81], v[130:133], v[186:189], v[78:81]
	v_mfma_f32_16x16x32_bf16 v[74:77], v[138:141], v[186:189], v[74:77]
	v_mfma_f32_16x16x32_bf16 v[126:129], v[134:137], v[166:169], v[126:129]
	v_mfma_f32_16x16x32_bf16 v[122:125], v[142:145], v[166:169], v[122:125]
	v_mfma_f32_16x16x32_bf16 v[110:113], v[134:137], v[174:177], v[110:113]
	v_mfma_f32_16x16x32_bf16 v[106:109], v[142:145], v[174:177], v[106:109]
	v_mfma_f32_16x16x32_bf16 v[94:97], v[134:137], v[182:185], v[94:97]
	v_mfma_f32_16x16x32_bf16 v[90:93], v[142:145], v[182:185], v[90:93]
	v_mfma_f32_16x16x32_bf16 v[78:81], v[134:137], v[190:193], v[78:81]
	v_mfma_f32_16x16x32_bf16 v[74:77], v[142:145], v[190:193], v[74:77]
	s_setprio 0
	s_setprio 1
	v_mfma_f32_16x16x32_bf16 v[118:121], v[146:149], v[162:165], v[118:121]
	v_mfma_f32_16x16x32_bf16 v[114:117], v[154:157], v[162:165], v[114:117]
	v_mfma_f32_16x16x32_bf16 v[102:105], v[146:149], v[170:173], v[102:105]
	v_mfma_f32_16x16x32_bf16 v[98:101], v[154:157], v[170:173], v[98:101]
	v_mfma_f32_16x16x32_bf16 v[86:89], v[146:149], v[178:181], v[86:89]
	v_mfma_f32_16x16x32_bf16 v[82:85], v[154:157], v[178:181], v[82:85]
	v_mfma_f32_16x16x32_bf16 v[70:73], v[146:149], v[186:189], v[70:73]
	v_mfma_f32_16x16x32_bf16 v[66:69], v[154:157], v[186:189], v[66:69]
	v_mfma_f32_16x16x32_bf16 v[118:121], v[150:153], v[166:169], v[118:121]
	v_mfma_f32_16x16x32_bf16 v[114:117], v[158:161], v[166:169], v[114:117]
	v_mfma_f32_16x16x32_bf16 v[102:105], v[150:153], v[174:177], v[102:105]
	v_mfma_f32_16x16x32_bf16 v[98:101], v[158:161], v[174:177], v[98:101]
	v_mfma_f32_16x16x32_bf16 v[86:89], v[150:153], v[182:185], v[86:89]
	v_mfma_f32_16x16x32_bf16 v[82:85], v[158:161], v[182:185], v[82:85]
	v_mfma_f32_16x16x32_bf16 v[70:73], v[150:153], v[190:193], v[70:73]
	v_mfma_f32_16x16x32_bf16 v[66:69], v[158:161], v[190:193], v[66:69]
	s_setprio 0
	s_barrier
	s_add_i32 s49, s49, s31
	v_lshl_add_u64 v[194:195], s[20:21], 0, v[0:1]
	s_mov_b32 m0, s49
	ds_read_b128 v[162:165], v230 offset:16384
	ds_read_b128 v[166:169], v230 offset:17408
	ds_read_b128 v[170:173], v230 offset:18432
	ds_read_b128 v[174:177], v230 offset:19456
	ds_read_b128 v[178:181], v230 offset:20480
	ds_read_b128 v[182:185], v230 offset:21504
	ds_read_b128 v[186:189], v230 offset:22528
	ds_read_b128 v[190:193], v230 offset:23552
	global_load_lds_dwordx4 v[194:195], off
	s_add_i32 m0, s49, 0x2000
	s_add_u32 s50, s20, 0x20000
	v_lshl_add_u64 v[196:197], s[20:21], 0, v[202:203]
	s_addc_u32 s51, s21, 0
	s_add_i32 s49, s52, s31
	global_load_lds_dwordx4 v[196:197], off
	v_lshl_add_u64 v[210:211], s[50:51], 0, v[0:1]
	s_mov_b32 m0, s49
	v_lshl_add_u64 v[212:213], s[22:23], 0, v[200:201]
	global_load_lds_dwordx4 v[210:211], off
	v_lshl_add_u64 v[210:211], s[50:51], 0, v[202:203]
	s_add_i32 m0, s49, 0x2000
	s_nop 0
	global_load_lds_dwordx4 v[210:211], off
	v_lshl_add_u64 v[210:211], s[22:23], 0, v[198:199]
	s_mov_b32 m0, s34
	s_nop 0
	global_load_lds_dwordx4 v[210:211], off
	s_mov_b32 m0, s35
	s_nop 0
	global_load_lds_dwordx4 v[212:213], off
	s_waitcnt vmcnt(8)
	s_waitcnt lgkmcnt(0)
	s_barrier
; #define PG8_STAGE(bufoff, gbase, voff) do { _Pragma("unroll") for (int _i = 0; _i < 2; ++_i) \
;         __builtin_amdgcn_global_load_lds((const unsigned*)((const char*)(gbase) + (voff)[_i]), (LAS unsigned*)(lds + (bufoff) + ldsw + _i * 8192), 16, 0, 0); } while (0)
; #define PG8_LDA(dst, b, h) do { _Pragma("unroll") for (int m = 0; m < 4; ++m) _Pragma("unroll") for (int k = 0; k < 2; ++k) dst[m][k] = *(const LAS bf16x8*)(lds + PG8_SA(b, h) + aoff + m * 2048 + k * 1024); } while (0)
; #define PG8_LDB(dst, b, h) do { _Pragma("unroll") for (int n = 0; n < 2; ++n) _Pragma("unroll") for (int k = 0; k < 2; ++k) dst[n][k] = *(const LAS bf16x8*)(lds + PG8_SB(b, h) + boff + n * 2048 + k * 1024); } while (0)
; #define PG8_MMA(ai, bj, At, Bt) do { __builtin_amdgcn_s_setprio(1); _Pragma("unroll") for (int m = 0; m < 4; ++m) _Pragma("unroll") for (int n = 0; n < 2; ++n) _Pragma("unroll") for (int k = 0; k < 2; ++k) \
;         acc[ai][bj][m][n] = __builtin_amdgcn_mfma_f32_16x16x32_bf16(Bt[n][k], At[m][k], acc[ai][bj][m][n], 0, 0, 0); __builtin_amdgcn_s_setprio(0); } while (0)
; #define PG8_WAIT_V(n) asm volatile("s_waitcnt vmcnt(" #n ")" ::: "memory")
; #define PG8_WAIT_L(n) asm volatile("s_waitcnt lgkmcnt(" #n ")" ::: "memory")
; #define PG8_BAR __builtin_amdgcn_s_barrier()
; #define PG8_SCHED __builtin_amdgcn_sched_barrier(0)
; template <class Epi, class Sched, int KC, bool ALIGN_EPI = false, bool SP2 = false, bool ATILED = false>
; __device__ __forceinline__ void gemm_phase(LAS unsigned char* lds, const Gemm g, const Sched& S, const Epi& E, int wave_s) {
;     ...
;             PG8_WAIT_V(8); PG8_WAIT_L(0); PG8_BAR; PG8_MMA(1, 0, At, B0); PG8_MMA(1, 1, At, B1); PG8_BAR; PG8_SCHED;
;             PG8_LDB(B0, 1, 0); PG8_LDB(B1, 1, 1); PG8_SCHED; PG8_LDA(At, 1, 0); PG8_STAGE(PG8_SA(0, 1), a2 + hstepA, voffA);
;             PG8_WAIT_V(8); PG8_WAIT_L(0); PG8_BAR; PG8_MMA(0, 0, At, B0); PG8_MMA(0, 1, At, B1); PG8_BAR; PG8_SCHED;
;             PG8_LDA(At, 1, 1); PG8_STAGE(PG8_SB(1, 0), b3, voffB); PG8_STAGE(PG8_SB(1, 1), b3 + hstepB, voffB); PG8_STAGE(PG8_SA(1, 0), a3, voffA);
;             PG8_WAIT_V(8); PG8_WAIT_L(0); PG8_BAR; PG8_MMA(1, 0, At, B0); PG8_MMA(1, 1, At, B1); PG8_BAR; PG8_SCHED;
	s_setprio 1
	s_waitcnt lgkmcnt(0)
	v_mfma_f32_16x16x32_bf16 v[62:65], v[130:133], v[162:165], v[62:65]
	v_mfma_f32_16x16x32_bf16 v[58:61], v[138:141], v[162:165], v[58:61]
	v_mfma_f32_16x16x32_bf16 v[46:49], v[130:133], v[170:173], v[46:49]
	v_mfma_f32_16x16x32_bf16 v[42:45], v[138:141], v[170:173], v[42:45]
	v_mfma_f32_16x16x32_bf16 v[30:33], v[130:133], v[178:181], v[30:33]
	v_mfma_f32_16x16x32_bf16 v[26:29], v[138:141], v[178:181], v[26:29]
	v_mfma_f32_16x16x32_bf16 v[14:17], v[130:133], v[186:189], v[14:17]
	v_mfma_f32_16x16x32_bf16 v[10:13], v[138:141], v[186:189], v[10:13]
	v_mfma_f32_16x16x32_bf16 v[62:65], v[134:137], v[166:169], v[62:65]
	v_mfma_f32_16x16x32_bf16 v[58:61], v[142:145], v[166:169], v[58:61]
	v_mfma_f32_16x16x32_bf16 v[46:49], v[134:137], v[174:177], v[46:49]
	v_mfma_f32_16x16x32_bf16 v[42:45], v[142:145], v[174:177], v[42:45]
	v_mfma_f32_16x16x32_bf16 v[30:33], v[134:137], v[182:185], v[30:33]
	v_mfma_f32_16x16x32_bf16 v[26:29], v[142:145], v[182:185], v[26:29]
	v_mfma_f32_16x16x32_bf16 v[14:17], v[134:137], v[190:193], v[14:17]
	v_mfma_f32_16x16x32_bf16 v[10:13], v[142:145], v[190:193], v[10:13]
	s_setprio 0
	s_setprio 1
	v_mfma_f32_16x16x32_bf16 v[54:57], v[146:149], v[162:165], v[54:57]
	v_mfma_f32_16x16x32_bf16 v[50:53], v[154:157], v[162:165], v[50:53]
	v_mfma_f32_16x16x32_bf16 v[38:41], v[146:149], v[170:173], v[38:41]
	v_mfma_f32_16x16x32_bf16 v[34:37], v[154:157], v[170:173], v[34:37]
	v_mfma_f32_16x16x32_bf16 v[22:25], v[146:149], v[178:181], v[22:25]
	v_mfma_f32_16x16x32_bf16 v[18:21], v[154:157], v[178:181], v[18:21]
	v_mfma_f32_16x16x32_bf16 v[6:9], v[146:149], v[186:189], v[6:9]
	v_mfma_f32_16x16x32_bf16 v[2:5], v[154:157], v[186:189], v[2:5]
	v_mfma_f32_16x16x32_bf16 v[54:57], v[150:153], v[166:169], v[54:57]
	v_mfma_f32_16x16x32_bf16 v[50:53], v[158:161], v[166:169], v[50:53]
	v_mfma_f32_16x16x32_bf16 v[38:41], v[150:153], v[174:177], v[38:41]
	v_mfma_f32_16x16x32_bf16 v[34:37], v[158:161], v[174:177], v[34:37]
	v_mfma_f32_16x16x32_bf16 v[22:25], v[150:153], v[182:185], v[22:25]
	v_mfma_f32_16x16x32_bf16 v[18:21], v[158:161], v[182:185], v[18:21]
	v_mfma_f32_16x16x32_bf16 v[6:9], v[150:153], v[190:193], v[6:9]
	v_mfma_f32_16x16x32_bf16 v[2:5], v[158:161], v[190:193], v[2:5]
	s_setprio 0
	s_barrier
	s_add_i32 s49, 0, 0x18000
	s_add_i32 s50, 0, 0x1c000
	v_add_u32_e32 v142, s49, v229
	v_add_u32_e32 v158, s50, v229
	ds_read_b128 v[130:133], v142
	ds_read_b128 v[134:137], v142 offset:1024
	ds_read_b128 v[138:141], v142 offset:2048
	ds_read_b128 v[142:145], v142 offset:3072
	ds_read_b128 v[146:149], v158
	ds_read_b128 v[150:153], v158 offset:1024
	ds_read_b128 v[154:157], v158 offset:2048
	ds_read_b128 v[158:161], v158 offset:3072
	s_add_u32 s22, s22, 0x80000
	s_addc_u32 s23, s23, 0
	s_mov_b32 m0, s36
	v_lshl_add_u64 v[214:215], s[22:23], 0, v[198:199]
	ds_read_b128 v[162:165], v230 offset:32768
	ds_read_b128 v[166:169], v230 offset:33792
	ds_read_b128 v[170:173], v230 offset:34816
	ds_read_b128 v[174:177], v230 offset:35840
	ds_read_b128 v[178:181], v230 offset:36864
	ds_read_b128 v[182:185], v230 offset:37888
	ds_read_b128 v[186:189], v230 offset:38912
	ds_read_b128 v[190:193], v230 offset:39936
	global_load_lds_dwordx4 v[214:215], off
	v_lshl_add_u64 v[214:215], s[22:23], 0, v[200:201]
	s_mov_b32 m0, s37
	s_nop 0
	global_load_lds_dwordx4 v[214:215], off
	s_waitcnt vmcnt(8)
	s_waitcnt lgkmcnt(0)
	s_barrier
	s_setprio 1
	s_waitcnt lgkmcnt(0)
	v_mfma_f32_16x16x32_bf16 v[126:129], v[130:133], v[162:165], v[126:129]
	v_mfma_f32_16x16x32_bf16 v[122:125], v[138:141], v[162:165], v[122:125]
	v_mfma_f32_16x16x32_bf16 v[110:113], v[130:133], v[170:173], v[110:113]
	v_mfma_f32_16x16x32_bf16 v[106:109], v[138:141], v[170:173], v[106:109]
	v_mfma_f32_16x16x32_bf16 v[94:97], v[130:133], v[178:181], v[94:97]
	v_mfma_f32_16x16x32_bf16 v[90:93], v[138:141], v[178:181], v[90:93]
	v_mfma_f32_16x16x32_bf16 v[78:81], v[130:133], v[186:189], v[78:81]
	v_mfma_f32_16x16x32_bf16 v[74:77], v[138:141], v[186:189], v[74:77]
	v_mfma_f32_16x16x32_bf16 v[126:129], v[134:137], v[166:169], v[126:129]
	v_mfma_f32_16x16x32_bf16 v[122:125], v[142:145], v[166:169], v[122:125]
	v_mfma_f32_16x16x32_bf16 v[110:113], v[134:137], v[174:177], v[110:113]
	v_mfma_f32_16x16x32_bf16 v[106:109], v[142:145], v[174:177], v[106:109]
	v_mfma_f32_16x16x32_bf16 v[94:97], v[134:137], v[182:185], v[94:97]
	v_mfma_f32_16x16x32_bf16 v[90:93], v[142:145], v[182:185], v[90:93]
	v_mfma_f32_16x16x32_bf16 v[78:81], v[134:137], v[190:193], v[78:81]
	v_mfma_f32_16x16x32_bf16 v[74:77], v[142:145], v[190:193], v[74:77]
	s_setprio 0
	s_setprio 1
	v_mfma_f32_16x16x32_bf16 v[118:121], v[146:149], v[162:165], v[118:121]
	v_mfma_f32_16x16x32_bf16 v[114:117], v[154:157], v[162:165], v[114:117]
	v_mfma_f32_16x16x32_bf16 v[102:105], v[146:149], v[170:173], v[102:105]
	v_mfma_f32_16x16x32_bf16 v[98:101], v[154:157], v[170:173], v[98:101]
	v_mfma_f32_16x16x32_bf16 v[86:89], v[146:149], v[178:181], v[86:89]
	v_mfma_f32_16x16x32_bf16 v[82:85], v[154:157], v[178:181], v[82:85]
	v_mfma_f32_16x16x32_bf16 v[70:73], v[146:149], v[186:189], v[70:73]
	v_mfma_f32_16x16x32_bf16 v[66:69], v[154:157], v[186:189], v[66:69]
	v_mfma_f32_16x16x32_bf16 v[118:121], v[150:153], v[166:169], v[118:121]
	v_mfma_f32_16x16x32_bf16 v[114:117], v[158:161], v[166:169], v[114:117]
	v_mfma_f32_16x16x32_bf16 v[102:105], v[150:153], v[174:177], v[102:105]
	v_mfma_f32_16x16x32_bf16 v[98:101], v[158:161], v[174:177], v[98:101]
	v_mfma_f32_16x16x32_bf16 v[86:89], v[150:153], v[182:185], v[86:89]
	v_mfma_f32_16x16x32_bf16 v[82:85], v[158:161], v[182:185], v[82:85]
	v_mfma_f32_16x16x32_bf16 v[70:73], v[150:153], v[190:193], v[70:73]
	v_mfma_f32_16x16x32_bf16 v[66:69], v[158:161], v[190:193], v[66:69]
	s_setprio 0
	s_barrier
; #define PG8_STAGE(bufoff, gbase, voff) do { _Pragma("unroll") for (int _i = 0; _i < 2; ++_i) \
;         __builtin_amdgcn_global_load_lds((const unsigned*)((const char*)(gbase) + (voff)[_i]), (LAS unsigned*)(lds + (bufoff) + ldsw + _i * 8192), 16, 0, 0); } while (0)
; #define PG8_LDA(dst, b, h) do { _Pragma("unroll") for (int m = 0; m < 4; ++m) _Pragma("unroll") for (int k = 0; k < 2; ++k) dst[m][k] = *(const LAS bf16x8*)(lds + PG8_SA(b, h) + aoff + m * 2048 + k * 1024); } while (0)
; #define PG8_BAR __builtin_amdgcn_s_barrier()
; template <class Epi, class Sched, int KC, bool ALIGN_EPI = false, bool SP2 = false, bool ATILED = false>
; __device__ __forceinline__ void gemm_phase(LAS unsigned char* lds, const Gemm g, const Sched& S, const Epi& E, int wave_s) {
;     ...
;             PG8_LDA(At, 1, 1); PG8_STAGE(PG8_SB(1, 0), b3, voffB); PG8_STAGE(PG8_SB(1, 1), b3 + hstepB, voffB); PG8_STAGE(PG8_SA(1, 0), a3, voffA);
;             PG8_WAIT_V(8); PG8_WAIT_L(0); PG8_BAR; PG8_MMA(1, 0, At, B0); PG8_MMA(1, 1, At, B1); PG8_BAR; PG8_SCHED;
;             } else {
;             PG8_LDB(B0, 0, 0); PG8_SCHED; PG8_LDA(At, 0, 0); PG8_STAGE(PG8_SA(1, 1), a1 + hstepA, voffA);
;             PG8_WAIT_L(8); PG8_BAR; PG8_WAIT_L(0); PG8_MMA(0, 0, At, B0); PG8_BAR; PG8_SCHED;
;             PG8_LDB(B1, 0, 1); PG8_STAGE(PG8_SB(0, 0), b2, voffB);
;             PG8_BAR; PG8_WAIT_L(0); PG8_MMA(0, 1, At, B1); PG8_BAR;
;             PG8_LDA(At, 0, 1); PG8_STAGE(PG8_SA(0, 0), a2, voffA);
;             PG8_BAR; PG8_WAIT_L(0); PG8_MMA(1, 0, At, B0); PG8_BAR; PG8_SCHED;
;             PG8_STAGE(PG8_SB(0, 1), b2 + hstepB, voffB);
;             PG8_WAIT_V(6); PG8_BAR; PG8_MMA(1, 1, At, B1); PG8_BAR;
;             PG8_LDB(B0, 1, 0); PG8_SCHED; PG8_LDA(At, 1, 0); PG8_STAGE(PG8_SA(0, 1), a2 + hstepA, voffA);
;             PG8_WAIT_L(8); PG8_BAR; PG8_WAIT_L(0); PG8_MMA(0, 0, At, B0); PG8_BAR; PG8_SCHED;
;             PG8_LDB(B1, 1, 1); PG8_STAGE(PG8_SB(1, 0), b3, voffB);
;             PG8_BAR; PG8_WAIT_L(0); PG8_MMA(0, 1, At, B1); PG8_BAR;
;             PG8_LDA(At, 1, 1); PG8_STAGE(PG8_SA(1, 0), a3, voffA);
;             PG8_BAR; PG8_WAIT_L(0); PG8_MMA(1, 0, At, B0); PG8_BAR; PG8_SCHED;
;             PG8_STAGE(PG8_SB(1, 1), b3 + hstepB, voffB);
;             PG8_WAIT_V(6); PG8_BAR; PG8_MMA(1, 1, At, B1); PG8_BAR;
;             }
;         }
;         if constexpr (ALIGN_EPI) { if (wr == 0) PG8_BAR; }
	s_add_i32 s22, s49, s31
	v_lshl_add_u64 v[194:195], v[194:195], 0, s[96:97]
	s_mov_b32 m0, s22
	ds_read_b128 v[162:165], v230 offset:49152
	ds_read_b128 v[166:169], v230 offset:50176
	ds_read_b128 v[170:173], v230 offset:51200
	ds_read_b128 v[174:177], v230 offset:52224
	ds_read_b128 v[178:181], v230 offset:53248
	ds_read_b128 v[182:185], v230 offset:54272
	ds_read_b128 v[186:189], v230 offset:55296
	ds_read_b128 v[190:193], v230 offset:56320
	global_load_lds_dwordx4 v[194:195], off
	s_add_i32 m0, s22, 0x2000
	s_add_u32 s20, s20, 0x20080
	v_lshl_add_u64 v[194:195], v[196:197], 0, s[96:97]
	s_addc_u32 s21, s21, 0
	s_add_i32 s22, s50, s31
	global_load_lds_dwordx4 v[194:195], off
	v_lshl_add_u64 v[194:195], s[20:21], 0, v[0:1]
	s_mov_b32 m0, s22
	s_nop 0
	global_load_lds_dwordx4 v[194:195], off
	v_lshl_add_u64 v[194:195], s[20:21], 0, v[202:203]
	s_add_i32 m0, s22, 0x2000
	s_nop 0
	global_load_lds_dwordx4 v[194:195], off
	v_lshl_add_u64 v[194:195], v[210:211], 0, s[96:97]
	s_mov_b32 m0, s41
	s_nop 0
	global_load_lds_dwordx4 v[194:195], off
	v_lshl_add_u64 v[194:195], v[212:213], 0, s[96:97]
	s_mov_b32 m0, s42
	s_nop 0
	global_load_lds_dwordx4 v[194:195], off
	s_waitcnt vmcnt(8)
	s_waitcnt lgkmcnt(0)
	s_barrier
	s_setprio 1
	s_waitcnt lgkmcnt(0)
	v_mfma_f32_16x16x32_bf16 v[62:65], v[130:133], v[162:165], v[62:65]
	v_mfma_f32_16x16x32_bf16 v[58:61], v[138:141], v[162:165], v[58:61]
	v_mfma_f32_16x16x32_bf16 v[46:49], v[130:133], v[170:173], v[46:49]
	v_mfma_f32_16x16x32_bf16 v[42:45], v[138:141], v[170:173], v[42:45]
	v_mfma_f32_16x16x32_bf16 v[30:33], v[130:133], v[178:181], v[30:33]
	v_mfma_f32_16x16x32_bf16 v[26:29], v[138:141], v[178:181], v[26:29]
	v_mfma_f32_16x16x32_bf16 v[14:17], v[130:133], v[186:189], v[14:17]
	v_mfma_f32_16x16x32_bf16 v[10:13], v[138:141], v[186:189], v[10:13]
	v_mfma_f32_16x16x32_bf16 v[62:65], v[134:137], v[166:169], v[62:65]
	v_mfma_f32_16x16x32_bf16 v[58:61], v[142:145], v[166:169], v[58:61]
	v_mfma_f32_16x16x32_bf16 v[46:49], v[134:137], v[174:177], v[46:49]
	v_mfma_f32_16x16x32_bf16 v[42:45], v[142:145], v[174:177], v[42:45]
	v_mfma_f32_16x16x32_bf16 v[30:33], v[134:137], v[182:185], v[30:33]
	v_mfma_f32_16x16x32_bf16 v[26:29], v[142:145], v[182:185], v[26:29]
	v_mfma_f32_16x16x32_bf16 v[14:17], v[134:137], v[190:193], v[14:17]
	v_mfma_f32_16x16x32_bf16 v[10:13], v[142:145], v[190:193], v[10:13]
	s_setprio 0
	s_setprio 1
	v_mfma_f32_16x16x32_bf16 v[54:57], v[146:149], v[162:165], v[54:57]
	v_mfma_f32_16x16x32_bf16 v[50:53], v[154:157], v[162:165], v[50:53]
	v_mfma_f32_16x16x32_bf16 v[38:41], v[146:149], v[170:173], v[38:41]
	v_mfma_f32_16x16x32_bf16 v[34:37], v[154:157], v[170:173], v[34:37]
	v_mfma_f32_16x16x32_bf16 v[22:25], v[146:149], v[178:181], v[22:25]
	v_mfma_f32_16x16x32_bf16 v[18:21], v[154:157], v[178:181], v[18:21]
	v_mfma_f32_16x16x32_bf16 v[6:9], v[146:149], v[186:189], v[6:9]
	v_mfma_f32_16x16x32_bf16 v[2:5], v[154:157], v[186:189], v[2:5]
	v_mfma_f32_16x16x32_bf16 v[54:57], v[150:153], v[166:169], v[54:57]
	v_mfma_f32_16x16x32_bf16 v[50:53], v[158:161], v[166:169], v[50:53]
	v_mfma_f32_16x16x32_bf16 v[38:41], v[150:153], v[174:177], v[38:41]
	v_mfma_f32_16x16x32_bf16 v[34:37], v[158:161], v[174:177], v[34:37]
	v_mfma_f32_16x16x32_bf16 v[22:25], v[150:153], v[182:185], v[22:25]
	v_mfma_f32_16x16x32_bf16 v[18:21], v[158:161], v[182:185], v[18:21]
	v_mfma_f32_16x16x32_bf16 v[6:9], v[150:153], v[190:193], v[6:9]
	v_mfma_f32_16x16x32_bf16 v[2:5], v[158:161], v[190:193], v[2:5]
	s_setprio 0
	s_barrier
	s_add_i32 s48, s48, 2
	s_add_u32 s46, s46, 0x100
	s_addc_u32 s47, s47, 0
	s_add_u32 s18, s18, 0x100
	s_addc_u32 s19, s19, 0
	s_cmp_gt_u32 s48, 29
	s_cbranch_scc0 .LBB0_1021
	s_cmpk_gt_u32 s26, 0xff
	s_cbranch_scc1 .Lout_epi
	s_barrier
; #define GAS __attribute__((address_space(1)))
; DI unsigned cvtpk(float lo, float hi) { unsigned r; asm volatile("v_cvt_pk_bf16_f32 %0, %1, %2" : "=v"(r) : "v"(lo), "v"(hi)); return r; }
;     DI void operator()(const f32x4 (&acc)[2][2][4][2], const Unit& u, int wr, int wc, int fr, int fq) const {
;         const int row0 = u.pm * BM + wr * 64 + fr, col0 = u.pn * BM + wc * 64 + 8 * fq;
;         const size_t hbase = (size_t)u.pn * ((size_t)M * 256) + wc * 64 + 8 * fq;
;         u32x4 H[2][4][2];
; #pragma unroll
;         for (int ai = 0; ai < 2; ++ai)
; #pragma unroll
;             for (int m = 0; m < 4; ++m)
; #pragma unroll
;                 for (int bj = 0; bj < 2; ++bj) H[ai][m][bj] = *(const GAS u32x4*)(hi + hbase + (size_t)(row0 + ai * HALF + m * 16) * 256 + bj * 32);
;         asm volatile("" ::: "memory");
; #pragma unroll
;         for (int ai = 0; ai < 2; ++ai) {
; #pragma unroll
;             for (int m = 0; m < 4; ++m) {
;                 const int r = row0 + ai * HALF + m * 16; const size_t off = (size_t)r * DM + col0; float ss = 0.f;
; #pragma unroll
;                 for (int bj = 0; bj < 2; ++bj) {
;                     const u32x4 h = H[ai][m][bj];
;                     const f32x4 a0 = acc[ai][bj][m][0], a1 = acc[ai][bj][m][1];
;                     float v[8];
;                     v[0] = bflo(h.x) + a0[0] * scale; v[1] = bfhi(h.x) + a0[1] * scale;
;                     v[2] = bflo(h.y) + a0[2] * scale; v[3] = bfhi(h.y) + a0[3] * scale;
;                     v[4] = bflo(h.z) + a1[0] * scale; v[5] = bfhi(h.z) + a1[1] * scale;
;                     v[6] = bflo(h.w) + a1[2] * scale; v[7] = bfhi(h.w) + a1[3] * scale;
; #pragma unroll
;                     for (int e = 0; e < 8; ++e) ss += v[e] * v[e];
;                     u32x4 nh;
;                     nh.x = cvtpk(v[0], v[1]); nh.y = cvtpk(v[2], v[3]); nh.z = cvtpk(v[4], v[5]); nh.w = cvtpk(v[6], v[7]);
;                     *(GAS u32x4*)(hi + hbase + (size_t)r * 256 + bj * 32) = nh;
;                     if (out) { *(GAS f32x4*)(out + off + bj * 32) = (f32x4){v[0], v[1], v[2], v[3]}; *(GAS f32x4*)(out + off + bj * 32 + 4) = (f32x4){v[4], v[5], v[6], v[7]}; }
;                 }
;                 ss = sum_xor32(sum_xor16(ss));
;                 if (fq == 0) ((GAS float*)rowss)[(size_t)(u.pn * 4 + wc) * M + r] = ss;
.Lout_epi:
	v_lshl_add_u32 v210, s16, 8, v228
	s_ashr_i32 s15, s14, 31
	s_lshl_b64 s[16:17], s[14:15], 23
	v_ashrrev_i32_e32 v211, 31, v210
	v_lshl_add_u64 v[130:131], v[204:205], 0, s[16:17]
	v_lshlrev_b64 v[132:133], 9, v[210:211]
	v_lshl_add_u64 v[226:227], v[130:131], 0, v[132:133]
	global_load_dwordx4 v[190:193], v[226:227], off
	global_load_dwordx4 v[186:189], v[226:227], off offset:64
	v_or_b32_e32 v132, 16, v210
	v_ashrrev_i32_e32 v133, 31, v132
	v_lshlrev_b64 v[132:133], 9, v[132:133]
	v_lshl_add_u64 v[224:225], v[130:131], 0, v[132:133]
	v_or_b32_e32 v132, 32, v210
	v_ashrrev_i32_e32 v133, 31, v132
	v_lshlrev_b64 v[132:133], 9, v[132:133]
	v_lshl_add_u64 v[222:223], v[130:131], 0, v[132:133]
	v_or_b32_e32 v132, 48, v210
	v_ashrrev_i32_e32 v133, 31, v132
	v_lshlrev_b64 v[132:133], 9, v[132:133]
	s_mov_b32 s3, 0x10000
	v_lshl_add_u64 v[220:221], v[130:131], 0, v[132:133]
	v_add_co_u32_e32 v130, vcc, s3, v226
	s_mov_b64 s[16:17], 0x10000
	s_nop 0
	v_addc_co_u32_e32 v131, vcc, 0, v227, vcc
	s_mov_b32 s3, 0x12000
	global_load_dwordx4 v[182:185], v[224:225], off
	global_load_dwordx4 v[178:181], v[224:225], off offset:64
	global_load_dwordx4 v[174:177], v[222:223], off
	global_load_dwordx4 v[170:173], v[222:223], off offset:64
	global_load_dwordx4 v[166:169], v[220:221], off
	global_load_dwordx4 v[162:165], v[220:221], off offset:64
	v_lshl_add_u64 v[218:219], v[226:227], 0, s[16:17]
	global_load_dwordx4 v[158:161], v[130:131], off
	global_load_dwordx4 v[150:153], v[218:219], off offset:64
	v_add_co_u32_e32 v130, vcc, s3, v226
	s_mov_b64 s[16:17], 0x12000
	s_nop 0
	v_addc_co_u32_e32 v131, vcc, 0, v227, vcc
	s_mov_b32 s3, 0x14000
	v_lshl_add_u64 v[216:217], v[226:227], 0, s[16:17]
	global_load_dwordx4 v[154:157], v[130:131], off
	global_load_dwordx4 v[146:149], v[216:217], off offset:64
	v_add_co_u32_e32 v130, vcc, s3, v226
	s_mov_b64 s[16:17], 0x14000
	s_nop 0
	v_addc_co_u32_e32 v131, vcc, 0, v227, vcc
	s_mov_b32 s3, 0x16000
	v_lshl_add_u64 v[214:215], v[226:227], 0, s[16:17]
	global_load_dwordx4 v[142:145], v[130:131], off
	global_load_dwordx4 v[134:137], v[214:215], off offset:64
	v_add_co_u32_e32 v130, vcc, s3, v226
	s_mov_b64 s[16:17], 0x16000
	s_nop 0
	v_addc_co_u32_e32 v131, vcc, 0, v227, vcc
	v_lshl_add_u64 v[212:213], v[226:227], 0, s[16:17]
	global_load_dwordx4 v[138:141], v[130:131], off
	s_nop 0
	global_load_dwordx4 v[130:133], v[212:213], off offset:64
	s_lshl_b32 s3, s14, 2
	s_or_b32 s14, s3, s40
	s_ashr_i32 s15, s14, 31
	s_lshl_b64 s[14:15], s[14:15], 16
	s_waitcnt vmcnt(0)
	v_lshlrev_b32_e32 v194, 16, v190
	v_and_b32_e32 v190, 0xffff0000, v190
	v_add_f32_e32 v127, v127, v190
	v_lshlrev_b32_e32 v190, 16, v191
	v_add_f32_e32 v128, v128, v190
	v_and_b32_e32 v190, 0xffff0000, v191
	v_add_f32_e32 v129, v129, v190
	v_lshlrev_b32_e32 v190, 16, v192
	v_add_f32_e32 v190, v122, v190
	v_and_b32_e32 v122, 0xffff0000, v192
	v_add_f32_e32 v191, v123, v122
	v_lshlrev_b32_e32 v122, 16, v193
	v_add_f32_e32 v126, v126, v194
	v_add_f32_e32 v192, v124, v122
	v_and_b32_e32 v122, 0xffff0000, v193
	v_mul_f32_e32 v193, v127, v127
	v_fmac_f32_e32 v193, v126, v126
	v_fmac_f32_e32 v193, v128, v128
	v_fmac_f32_e32 v193, v129, v129
	v_fmac_f32_e32 v193, v190, v190
	v_fmac_f32_e32 v193, v191, v191
	v_add_f32_e32 v125, v125, v122
	v_fmac_f32_e32 v193, v192, v192
	v_cvt_pk_bf16_f32 v122, v126, v127
	v_fmac_f32_e32 v193, v125, v125
	v_cvt_pk_bf16_f32 v123, v128, v129
	v_cvt_pk_bf16_f32 v124, v190, v191
	v_cvt_pk_bf16_f32 v125, v192, v125
	global_store_dwordx4 v[226:227], v[122:125], off
	s_nop 1
	v_lshlrev_b32_e32 v122, 16, v186
	v_add_f32_e32 v118, v118, v122
	v_and_b32_e32 v122, 0xffff0000, v186
	v_add_f32_e32 v119, v119, v122
	v_lshlrev_b32_e32 v122, 16, v187
	v_fmac_f32_e32 v193, v118, v118
	v_add_f32_e32 v120, v120, v122
	v_and_b32_e32 v122, 0xffff0000, v187
	v_fmac_f32_e32 v193, v119, v119
	v_add_f32_e32 v121, v121, v122
	v_lshlrev_b32_e32 v122, 16, v188
	v_fmac_f32_e32 v193, v120, v120
	v_add_f32_e32 v122, v114, v122
	v_and_b32_e32 v114, 0xffff0000, v188
	v_fmac_f32_e32 v193, v121, v121
	v_add_f32_e32 v123, v115, v114
	v_lshlrev_b32_e32 v114, 16, v189
	v_fmac_f32_e32 v193, v122, v122
	v_add_f32_e32 v124, v116, v114
	v_and_b32_e32 v114, 0xffff0000, v189
	v_fmac_f32_e32 v193, v123, v123
	v_add_f32_e32 v117, v117, v114
	v_fmac_f32_e32 v193, v124, v124
	v_fmac_f32_e32 v193, v117, v117
	v_cvt_pk_bf16_f32 v114, v118, v119
	v_cvt_pk_bf16_f32 v115, v120, v121
	v_cvt_pk_bf16_f32 v116, v122, v123
	v_cvt_pk_bf16_f32 v117, v124, v117
	global_store_dwordx4 v[226:227], v[114:117], off offset:64
	s_nop 1
	v_mov_b32_e32 v114, v193
	s_nop 1
	v_permlane16_swap_b32_e32 v193, v114
	v_add_f32_e32 v114, v193, v114
	v_mov_b32_e32 v115, v114
	s_nop 1
	v_permlane32_swap_b32_e32 v114, v115
	s_and_saveexec_b64 s[16:17], s[4:5]
	s_cbranch_execz .LBB0_1024
	s_add_u32 s18, s38, s14
	s_addc_u32 s19, s39, s15
	v_lshl_add_u64 v[116:117], v[210:211], 2, s[18:19]
	v_add_f32_e32 v114, v114, v115
	global_store_dword v[116:117], v114, off

; #define PG8_WAIT_V(n) asm volatile("s_waitcnt vmcnt(" #n ")" ::: "memory")
; #define PG8_BAR __builtin_amdgcn_s_barrier()
; template <class Epi, class Sched, int KC, bool ALIGN_EPI = false, bool SP2 = false, bool ATILED = false>
; __device__ __forceinline__ void gemm_phase(LAS unsigned char* lds, const Gemm g, const Sched& S, const Epi& E, int wave_s) {
;     ...
;     PG8_WAIT_V(0);
;     if constexpr (!ALIGN_EPI) { if (wr == 0) PG8_BAR; }
;     PG8_BAR;
.LBB0_1038:
	s_waitcnt vmcnt(0)
.LBB0_1040:
	s_barrier
